# prologue: FFT constant matrix slices on workgroups 192..223 (fourier-out fold workgroups, which have slack) instead of 128..159 (F-weight fold workgroups, the prologue's critical path)
# speedup vs baseline: 1.0022x; 1.0022x over previous
; __device__ __forceinline__ unsigned f2bf(float f) { unsigned u = __builtin_bit_cast(unsigned, f); return (u + 0x7fffu + ((u >> 16) & 1u)) >> 16; }
; __device__ __forceinline__ void prologue(const Args& A, LAS unsigned char* lds, int vcu, int G, const int tid) {
;     ...
;     const int vf = vcu - (G - 3);
;     if (vf == 0 || vf == 1) {
;         bf16_t* Mx = (bf16_t*)(ws + (vf == 0 ? WS_M1 : WS_M2));
;         for (int i = tid; i < 256 * 128; i += 512) { const int r = i >> 7, kap = i & 127, part = kap >> 6, nn = kap & 63; float v = 0.f;
;             if (vf == 0) { if (r < 64) { const float ph = (float)((r * nn) & 63) * (1.0f / 32.0f); v = part == 0 ? cospif(ph) : -sinpif(ph); }
;                             else if (r >= 128 && r < 192) { const float ph = (float)(((r - 128) * nn) & 63) * (1.0f / 32.0f); v = part == 0 ? -sinpif(ph) : -cospif(ph); } }
;             else { if (r < 64) { const float ph = (float)((r * nn) & 63) * (1.0f / 32.0f); v = part == 0 ? cospif(ph) : sinpif(ph); } }
;             Mx[i] = (bf16_t)f2bf(v); }
.LBB0_21:
	s_add_u32 s64, s94, 0x1000
	s_addc_u32 s65, s95, 0
	s_lshl_b32 s96, s33, 3
	s_add_u32 s50, s94, 0x83c40
	s_addc_u32 s51, s95, 0
	v_writelane_b32 v254, s92, 40
	s_cmp_lt_i32 s2, 1
	s_cselect_b64 s[0:1], -1, 0
	v_writelane_b32 v254, s93, 41
	v_writelane_b32 v254, s94, 42
	s_cmp_gt_i32 s3, 0
	v_writelane_b32 v254, s95, 43
	s_cselect_b64 s[2:3], -1, 0
	v_writelane_b32 v254, s63, 44
	s_and_b64 s[30:31], s[0:1], s[2:3]
	v_writelane_b32 v254, s64, 45
	s_andn2_b64 vcc, exec, s[30:31]
	s_nop 0
	v_writelane_b32 v254, s65, 46
	s_cbranch_vccnz .LBB0_185
	s_add_i32 s0, s33, -3
	v_readlane_b32 s1, v254, 7
	s_sub_i32 s2, s1, s0
	s_sub_i32 s52, s1, 0xc0
	s_and_b32 s3, s52, 15
	s_lshl_b32 s3, s3, 11
	s_cmp_lt_u32 s52, 32
	s_cselect_b64 s[0:1], -1, 0
	s_cselect_b32 s3, s3, 0
	s_cmp_lt_u32 s52, 16
	s_cselect_b64 s[18:19], 0, -1
	s_cselect_b64 s[52:53], -1, 0
	v_mov_b32_e32 v0, v200
	v_ashrrev_i32_e32 v18, 6, v0
	s_andn2_b64 vcc, exec, s[0:1]
	v_readfirstlane_b32 s17, v18
	v_add_u32_e32 v0, s3, v0
	s_addk_i32 s3, 0x800
	s_mov_b64 s[0:1], -1
	s_cbranch_vccz .LBB0_29
	s_cmp_lg_u32 s2, 2
	s_cbranch_scc1 .LBB0_28
	s_movk_i32 s0, 0x1000
	v_cmp_gt_i32_e32 vcc, s0, v0
	s_and_saveexec_b64 s[0:1], vcc
	s_cbranch_execz .LBB0_27
	v_ashrrev_i32_e32 v1, 31, v0
	v_lshl_add_u64 v[2:3], v[0:1], 3, s[94:95]
	s_mov_b64 s[2:3], 0xb0000
	v_lshl_add_u64 v[2:3], v[2:3], 0, s[2:3]
	s_mov_b64 s[2:3], 0
	s_mov_b32 s6, 0x7f800000
	v_mov_b32_e32 v1, 0xbf1f24be
	v_mov_b32_e32 v4, 0x3e642e9d
	s_movk_i32 s7, 0x1f8
	v_mov_b32_e32 v5, 0x7fc00000
	s_mov_b64 s[4:5], 0x1000
	s_movk_i32 s8, 0xdff
	v_mov_b32_e32 v6, v0
